# SSD chunk loop: z loads issued right after barrier 1 (conv temporaries renamed v178-185 -> v190-197), epilogue waits vmcnt(12) / (0) on last chunk
# speedup vs baseline: 1.0078x; 1.0078x over previous
; #define GAS __attribute__((address_space(1)))
; __device__ __forceinline__ void ssd_stream(const Frame& F, const Args& A, int sidx) {
;     ...
;         __syncthreads();
; #pragma unroll
;         for (int q4 = 0; q4 < 4; ++q4) { v2u o; o.x = pg8::cvt_pk_bf16(st[4 * q4], st[4 * q4 + 1]); o.y = pg8::cvt_pk_bf16(st[4 * q4 + 2], st[4 * q4 + 3]);
;             *(LAS v2u*)(ST + (32 * pt + r32) * BS_ + (32 * nt + 8 * q4 + 4 * hh) * 2) = o; }
;         {
;             const float aL = arr[127];
; #pragma unroll
;             for (int i = 0; i < 2; ++i) { *(LAS v4u*)(XST + xdst + 64 * i * XS_) = pfx[i]; if (lane < 24) *(LAS v4u*)(HAL + (3 * i + (lane >> 3)) * XS_ + 16 * (lane & 7)) = pfh[i]; }
;             v4u rw[2][4];
; #pragma unroll
;             for (int i = 0; i < 2; ++i)
; #pragma unroll
;                 for (int k = 0; k < 4; ++k) { const int lr = (lane >> 3) + k - 3;
;                     LAS unsigned char* src = lr >= 0 ? XST + (8 * w + lr + 64 * i) * XS_ + 16 * (lane & 7) : HAL + (3 * i + 3 + lr) * XS_ + 16 * (lane & 7);
;                     rw[i][k] = *(LAS v4u*)src; }
;             f32x4 cwa[5], cwb[5];
; #pragma unroll
;             for (int k = 0; k < 5; ++k) { cwa[k] = *(LAS f32x4*)(CWL + 64 * k + 8 * (lane & 7)); cwb[k] = *(LAS f32x4*)(CWL + 64 * k + 8 * (lane & 7) + 4); }
;             asm volatile("s_waitcnt lgkmcnt(0)" ::: "memory");
; #pragma unroll
;             for (int i = 0; i < 2; ++i) {
;                 const int row = (tid >> 3) + 64 * i;
;                 float y[8];
; #pragma unroll
;                 for (int e = 0; e < 8; ++e) y[e] = e < 4 ? cwa[4][e] : cwb[4][e - 4];
; #pragma unroll
;                 for (int k = 0; k < 4; ++k) { const v4u r = rw[i][k];
;                     y[0] += cwa[k][0] * bflo(r.x); y[1] += cwa[k][1] * bfhi(r.x); y[2] += cwa[k][2] * bflo(r.y); y[3] += cwa[k][3] * bfhi(r.y);
;                     y[4] += cwb[k][0] * bflo(r.z); y[5] += cwb[k][1] * bfhi(r.z); y[6] += cwb[k][2] * bflo(r.w); y[7] += cwb[k][3] * bfhi(r.w); }
; #pragma unroll
;                 for (int e = 0; e < 8; ++e) y[e] = silu_f(y[e]);
;                 *(LAS bf16x8*)(XT + xdst + 64 * i * XS_) = packf8(y[0], y[1], y[2], y[3], y[4], y[5], y[6], y[7]);
;     ...
;         { const GAS unsigned char* zb = Zg + (size_t)t0 * 4096;
; #pragma unroll
;           for (int q4 = 0; q4 < 4; ++q4) zw[q4] = *(const GAS v2u*)(zb + 16 * q4 + zoff); }
.LBB0_1293:
	s_lshl_b32 s92, s5, 7
	s_lshl_b64 s[64:65], s[92:93], 12
	s_bitcmp1_b32 s5, 0
	s_waitcnt lgkmcnt(0)
	s_barrier
	v_lshl_add_u64 v[198:199], v[152:153], 0, s[64:65]
	global_load_dwordx2 v[184:185], v[198:199], off
	global_load_dwordx2 v[182:183], v[198:199], off offset:16
	global_load_dwordx2 v[180:181], v[198:199], off offset:32
	global_load_dwordx2 v[178:179], v[198:199], off offset:48
	v_cvt_pk_bf16_f32 v18, v2, v3
	s_cselect_b32 s66, 0x600, 0
	v_cvt_pk_bf16_f32 v19, v4, v5
	ds_write_b64 v223, v[18:19]
	v_cvt_pk_bf16_f32 v18, v6, v7
	v_cvt_pk_bf16_f32 v19, v8, v9
	ds_write_b64 v223, v[18:19] offset:16
	v_cvt_pk_bf16_f32 v18, v10, v11
	s_add_i32 s78, s66, 0
	v_cvt_pk_bf16_f32 v19, v12, v13
	ds_write_b64 v223, v[18:19] offset:32
	v_cvt_pk_bf16_f32 v18, v14, v15
	s_add_i32 s78, s78, 0x1e400
	v_cvt_pk_bf16_f32 v19, v16, v17
	ds_write_b64 v223, v[18:19] offset:48
	v_mov_b32_e32 v18, s78
	ds_read_b32 v106, v18 offset:508
	s_waitcnt vmcnt(13)
	ds_write_b128 v229, v[50:53] offset:18432
	s_and_saveexec_b64 s[26:27], s[6:7]
	s_xor_b64 s[26:27], exec, s[26:27]
	s_cbranch_execz .LBB0_1295
	s_waitcnt vmcnt(12)
	ds_write_b128 v229, v[62:65] offset:27648
.LBB0_1295:
	s_andn2_saveexec_b64 s[26:27], s[26:27]
	s_cbranch_execz .LBB0_1297
	ds_write_b128 v210, v[58:61]
	s_waitcnt vmcnt(12)
	ds_write_b128 v229, v[62:65] offset:27648
	ds_write_b128 v210, v[54:57] offset:432
.LBB0_1297:
	s_or_b64 exec, exec, s[26:27]
	ds_read_b128 v[108:111], v212
	ds_read_b128 v[112:115], v213
	ds_read_b128 v[116:119], v214
	ds_read_b128 v[120:123], v215
	ds_read_b128 v[34:37], v216
	ds_read_b128 v[38:41], v217
	ds_read_b128 v[22:25], v218
	ds_read_b128 v[26:29], v219
	ds_read_b128 v[98:101], v207
	ds_read_b128 v[42:45], v207 offset:16
	ds_read_b128 v[124:127], v207 offset:256
	ds_read_b128 v[128:131], v207 offset:272
	ds_read_b128 v[30:33], v207 offset:512
	ds_read_b128 v[18:21], v207 offset:528
	ds_read_b128 v[132:135], v207 offset:768
	ds_read_b128 v[190:193], v207 offset:784
	ds_read_b128 v[102:105], v207 offset:1024
	ds_read_b128 v[46:49], v207 offset:1040
	s_waitcnt lgkmcnt(14)
	v_lshlrev_b32_e32 v137, 16, v108
	v_lshlrev_b32_e32 v136, 16, v112
	s_waitcnt lgkmcnt(7)
	v_mov_b32_e32 v194, v124
	v_mov_b32_e32 v195, v98
	s_waitcnt lgkmcnt(0)
	v_lshl_add_u32 v107, v175, 2, s78
	s_waitcnt lgkmcnt(1)
	v_fma_f32 v98, v98, v137, v102
	v_fma_f32 v140, v124, v136, v98
	v_and_b32_e32 v137, 0xffff0000, v108
	v_and_b32_e32 v136, 0xffff0000, v112
	v_mov_b32_e32 v98, v125
	v_fma_f32 v108, v99, v137, v103
	v_fma_f32 v196, v125, v136, v108
	v_lshlrev_b32_e32 v125, 16, v109
	v_lshlrev_b32_e32 v124, 16, v113
	v_mov_b32_e32 v137, v100
	v_and_b32_e32 v109, 0xffff0000, v109
	v_fma_f32 v100, v100, v125, v104
	v_fma_f32 v197, v126, v124, v100
	v_and_b32_e32 v108, 0xffff0000, v113
	v_mov_b32_e32 v100, v127
	v_mov_b32_e32 v112, v128
	v_fma_f32 v109, v101, v109, v105
	v_fma_f32 v186, v127, v108, v109
	v_lshlrev_b32_e32 v109, 16, v110
	v_lshlrev_b32_e32 v108, 16, v114
	v_mov_b32_e32 v113, v42
	v_mov_b32_e32 v124, v130
	s_waitcnt lgkmcnt(0)
	v_fma_f32 v42, v42, v109, v46
	v_fma_f32 v128, v128, v108, v42
	v_and_b32_e32 v109, 0xffff0000, v110
	v_and_b32_e32 v108, 0xffff0000, v114
	v_mov_b32_e32 v42, v129
	v_mov_b32_e32 v125, v44
	v_fma_f32 v109, v43, v109, v47
	v_fma_f32 v110, v129, v108, v109
	v_lshlrev_b32_e32 v109, 16, v111
	v_lshlrev_b32_e32 v108, 16, v115
	v_mov_b32_e32 v114, v132
	v_fma_f32 v44, v44, v109, v48
	v_fma_f32 v129, v130, v108, v44
	v_and_b32_e32 v109, 0xffff0000, v111
	v_and_b32_e32 v108, 0xffff0000, v115
	v_mov_b32_e32 v44, v131
	v_mov_b32_e32 v115, v30
	v_fma_f32 v109, v45, v109, v49
	v_fma_f32 v111, v131, v108, v109
	v_lshlrev_b32_e32 v109, 16, v116
	v_lshlrev_b32_e32 v108, 16, v120
	v_fma_f32 v30, v30, v109, v140
	v_fma_f32 v130, v132, v108, v30
	v_and_b32_e32 v109, 0xffff0000, v116
	v_and_b32_e32 v108, 0xffff0000, v120
	v_mov_b32_e32 v30, v133
	v_mov_b32_e32 v127, v32
	v_fma_f32 v109, v31, v109, v196
	v_fma_f32 v131, v133, v108, v109
	v_lshlrev_b32_e32 v109, 16, v117
	v_lshlrev_b32_e32 v108, 16, v121
	v_fma_f32 v32, v32, v109, v197
	v_fma_f32 v132, v134, v108, v32
	v_and_b32_e32 v109, 0xffff0000, v117
	v_and_b32_e32 v108, 0xffff0000, v121
	v_mov_b32_e32 v117, v18
	v_fma_f32 v109, v33, v109, v186
	v_fma_f32 v133, v135, v108, v109
	v_lshlrev_b32_e32 v109, 16, v118
	v_lshlrev_b32_e32 v108, 16, v122
	v_fma_f32 v18, v18, v109, v128
	v_fma_f32 v128, v190, v108, v18
	v_and_b32_e32 v109, 0xffff0000, v118
	v_and_b32_e32 v108, 0xffff0000, v122
	v_mov_b32_e32 v121, v20
	v_fma_f32 v109, v19, v109, v110
	v_fma_f32 v110, v191, v108, v109
	v_lshlrev_b32_e32 v109, 16, v119
	v_lshlrev_b32_e32 v108, 16, v123
	v_mul_f32_e32 v122, 0xbfb8aa3b, v133
	v_fma_f32 v20, v20, v109, v129
	v_fma_f32 v118, v192, v108, v20
	v_and_b32_e32 v109, 0xffff0000, v119
	v_and_b32_e32 v108, 0xffff0000, v123
	v_mov_b32_e32 v20, v193
	v_mul_f32_e32 v119, 0xbfb8aa3b, v130
	v_fma_f32 v109, v21, v109, v111
	v_mul_f32_e32 v111, 0xbfb8aa3b, v131
	v_exp_f32_e32 v119, v119
	v_exp_f32_e32 v111, v111
	v_fma_f32 v108, v193, v108, v109
	v_exp_f32_e32 v122, v122
	v_add_f32_e32 v109, 1.0, v119
	v_add_f32_e32 v111, 1.0, v111
	v_rcp_f32_e32 v109, v109
	v_rcp_f32_e32 v111, v111
	v_mul_f32_e32 v119, 0xbfb8aa3b, v132
	v_exp_f32_e32 v119, v119
	v_mul_f32_e32 v123, v130, v109
	v_mul_f32_e32 v129, v131, v111
	v_add_f32_e32 v109, 1.0, v122
	v_mul_f32_e32 v111, 0xbfb8aa3b, v128
	v_mul_f32_e32 v122, 0xbfb8aa3b, v110
	v_rcp_f32_e32 v109, v109
	v_exp_f32_e32 v111, v111
	v_exp_f32_e32 v122, v122
	v_mul_f32_e32 v131, 0xbfb8aa3b, v108
	v_mul_f32_e32 v130, v133, v109
	v_add_f32_e32 v109, 1.0, v111
	v_add_f32_e32 v111, 1.0, v122
	v_mul_f32_e32 v122, 0xbfb8aa3b, v118
	v_exp_f32_e32 v122, v122
	v_exp_f32_e32 v131, v131
	v_add_f32_e32 v119, 1.0, v119
	v_rcp_f32_e32 v119, v119
	v_add_f32_e32 v122, 1.0, v122
	v_add_f32_e32 v131, 1.0, v131
	v_rcp_f32_e32 v109, v109
	v_rcp_f32_e32 v111, v111
	v_rcp_f32_e32 v122, v122
	v_rcp_f32_e32 v131, v131
	v_mul_f32_e32 v119, v132, v119
	v_mul_f32_e32 v128, v128, v109
	v_mul_f32_e32 v132, v110, v111
	v_mul_f32_e32 v118, v118, v122
	v_mul_f32_e32 v122, v108, v131
	v_cvt_pk_bf16_f32 v108, v123, v129
	v_cvt_pk_bf16_f32 v109, v119, v130
	v_cvt_pk_bf16_f32 v110, v128, v132
	v_cvt_pk_bf16_f32 v111, v118, v122
	ds_write_b128 v229, v[108:111]
	ds_read2st64_b32 v[108:109], v107 offset1:2
	s_cmp_lg_u32 s5, 63
	s_cselect_b64 s[60:61], -1, 0
	s_waitcnt lgkmcnt(0)
; __device__ __forceinline__ float ex2(float x) { return __builtin_amdgcn_exp2f(x); }
; #define GAS __attribute__((address_space(1)))
; #define LAS __attribute__((address_space(3)))
; __device__ __forceinline__ void ssd_stream(const Frame& F, const Args& A, int sidx) {
;     ...
;                 const float te = ex2(aL - arr[row]) * arr[128 + row];
;                 *(LAS bf16x8*)(XST + xdst + 64 * i * XS_) = packf8(y[0] * te, y[1] * te, y[2] * te, y[3] * te, y[4] * te, y[5] * te, y[6] * te, y[7] * te);
;             }
; #pragma unroll
;             for (int i = 0; i < 4; ++i) { *(LAS v4u*)(BT + bdst + 32 * i * BS_) = pfb[i]; *(LAS v4u*)(CT + bdst + 32 * i * BS_) = pfc[i]; }
;         }
;         v2u zw[4];
;         { const GAS unsigned char* zb = Zg + (size_t)t0 * 4096;
; #pragma unroll
;           for (int q4 = 0; q4 < 4; ++q4) zw[q4] = *(const GAS v2u*)(zb + 16 * q4 + zoff); }
;         if (ck < 63) {
;             const GAS unsigned char* xb = XCg + (size_t)(t0 + 128) * 6144; const GAS unsigned char* rb = XBg + (size_t)(t0 + 128) * 6144;
; #pragma unroll
;             for (int i = 0; i < 2; ++i) { pfx[i] = *(const GAS v4u*)(rb + (size_t)i * (64 * 6144) + xoff);
;                 if (lane < 24) pfh[i] = *(const GAS v4u*)(rb + (ptrdiff_t)(hrow + 64 * i) * 6144 + hoff); }
; #pragma unroll
;             for (int i = 0; i < 4; ++i) { pfb[i] = *(const GAS v4u*)(xb + (size_t)i * (32 * 6144) + boff); pfc[i] = *(const GAS v4u*)(xb + (size_t)i * (32 * 6144) + 1024 + boff); }
;             if (w == 0) { const GAS unsigned char* db = DTg + (size_t)(t0 + 128) * 128; pd0 = *(const GAS float*)(db + doff); pd1 = *(const GAS float*)(db + 128 + doff); }
	v_sub_f32_e32 v108, v106, v108
	v_exp_f32_e32 v108, v108
	s_cmp_eq_u32 s5, 63
	v_mul_f32_e32 v108, v109, v108
	v_mul_f32_e32 v109, v123, v108
	v_mul_f32_e32 v110, v129, v108
	v_mul_f32_e32 v111, v119, v108
	v_mul_f32_e32 v119, v130, v108
	v_mul_f32_e32 v123, v128, v108
	v_mul_f32_e32 v128, v132, v108
	v_mul_f32_e32 v118, v118, v108
	v_mul_f32_e32 v122, v122, v108
	v_cvt_pk_bf16_f32 v108, v109, v110
	v_cvt_pk_bf16_f32 v109, v111, v119
	v_cvt_pk_bf16_f32 v110, v123, v128
	v_cvt_pk_bf16_f32 v111, v118, v122
	ds_write_b128 v229, v[108:111] offset:18432
	v_lshlrev_b32_e32 v109, 16, v34
	v_lshlrev_b32_e32 v108, 16, v38
	v_fma_f32 v102, v195, v109, v102
	v_fma_f32 v102, v194, v108, v102
	v_and_b32_e32 v109, 0xffff0000, v34
	v_and_b32_e32 v108, 0xffff0000, v38
	v_fma_f32 v34, v99, v109, v103
	v_fma_f32 v38, v98, v108, v34
	v_lshlrev_b32_e32 v99, 16, v35
	v_lshlrev_b32_e32 v98, 16, v39
	v_and_b32_e32 v35, 0xffff0000, v35
	v_fma_f32 v34, v137, v99, v104
	v_fma_f32 v98, v126, v98, v34
	v_and_b32_e32 v34, 0xffff0000, v39
	v_fma_f32 v35, v101, v35, v105
	v_fma_f32 v39, v100, v34, v35
	v_lshlrev_b32_e32 v35, 16, v36
	v_lshlrev_b32_e32 v34, 16, v40
	v_fma_f32 v35, v113, v35, v46
	v_fma_f32 v46, v112, v34, v35
	v_and_b32_e32 v35, 0xffff0000, v36
	v_and_b32_e32 v34, 0xffff0000, v40
	v_fma_f32 v35, v43, v35, v47
	v_fma_f32 v36, v42, v34, v35
	v_lshlrev_b32_e32 v35, 16, v37
	v_lshlrev_b32_e32 v34, 16, v41
	v_fma_f32 v35, v125, v35, v48
	v_fma_f32 v40, v124, v34, v35
	v_and_b32_e32 v35, 0xffff0000, v37
	v_and_b32_e32 v34, 0xffff0000, v41
	v_fma_f32 v35, v45, v35, v49
	v_fma_f32 v37, v44, v34, v35
	v_lshlrev_b32_e32 v35, 16, v22
	v_lshlrev_b32_e32 v34, 16, v26
	v_fma_f32 v35, v115, v35, v102
	v_fma_f32 v41, v114, v34, v35
	v_and_b32_e32 v35, 0xffff0000, v22
	v_and_b32_e32 v34, 0xffff0000, v26
	v_fma_f32 v22, v31, v35, v38
	v_fma_f32 v26, v30, v34, v22
	v_lshlrev_b32_e32 v31, 16, v23
	v_lshlrev_b32_e32 v30, 16, v27
	v_and_b32_e32 v23, 0xffff0000, v23
	v_fma_f32 v22, v127, v31, v98
	v_fma_f32 v30, v134, v30, v22
	v_and_b32_e32 v22, 0xffff0000, v27
	v_fma_f32 v23, v33, v23, v39
	v_fma_f32 v27, v135, v22, v23
	v_lshlrev_b32_e32 v23, 16, v24
	v_lshlrev_b32_e32 v22, 16, v28
	v_fma_f32 v23, v117, v23, v46
	v_fma_f32 v31, v190, v22, v23
	v_and_b32_e32 v23, 0xffff0000, v24
	v_and_b32_e32 v22, 0xffff0000, v28
	v_mul_f32_e32 v24, 0xbfb8aa3b, v41
	v_fma_f32 v19, v19, v23, v36
	v_fma_f32 v22, v191, v22, v19
	v_lshlrev_b32_e32 v19, 16, v25
	v_lshlrev_b32_e32 v18, 16, v29
	v_exp_f32_e32 v24, v24
	v_fma_f32 v19, v121, v19, v40
	v_fma_f32 v23, v192, v18, v19
	v_and_b32_e32 v19, 0xffff0000, v25
	v_and_b32_e32 v18, 0xffff0000, v29
	v_pk_mul_f32 v[18:19], v[20:21], v[18:19]
	v_mul_f32_e32 v20, 0xbfb8aa3b, v26
	v_mul_f32_e32 v21, 0xbfb8aa3b, v30
	v_exp_f32_e32 v20, v20
	v_exp_f32_e32 v21, v21
	v_add_f32_e32 v19, v19, v37
	v_add_f32_e32 v18, v18, v19
	v_add_f32_e32 v19, 1.0, v24
	v_add_f32_e32 v20, 1.0, v20
	v_add_f32_e32 v21, 1.0, v21
	v_mul_f32_e32 v24, 0xbfb8aa3b, v27
	v_rcp_f32_e32 v19, v19
	v_rcp_f32_e32 v20, v20
	v_rcp_f32_e32 v21, v21
	v_exp_f32_e32 v24, v24
	v_mul_f32_e32 v25, v41, v19
	v_mul_f32_e32 v26, v26, v20
	v_mul_f32_e32 v28, v30, v21
	v_add_f32_e32 v19, 1.0, v24
	v_mul_f32_e32 v20, 0xbfb8aa3b, v31
	v_mul_f32_e32 v21, 0xbfb8aa3b, v22
	v_rcp_f32_e32 v19, v19
	v_exp_f32_e32 v20, v20
	v_exp_f32_e32 v21, v21
	v_mul_f32_e32 v24, v27, v19
	v_add_f32_e32 v19, 1.0, v20
	v_add_f32_e32 v20, 1.0, v21
	v_mul_f32_e32 v21, 0xbfb8aa3b, v23
	v_mul_f32_e32 v27, 0xbfb8aa3b, v18
	v_exp_f32_e32 v21, v21
	v_exp_f32_e32 v27, v27
	v_rcp_f32_e32 v19, v19
	v_rcp_f32_e32 v20, v20
	v_add_f32_e32 v21, 1.0, v21
	v_add_f32_e32 v27, 1.0, v27
	v_rcp_f32_e32 v21, v21
	v_rcp_f32_e32 v27, v27
	v_mul_f32_e32 v29, v31, v19
	v_mul_f32_e32 v22, v22, v20
	v_mul_f32_e32 v23, v23, v21
	v_mul_f32_e32 v27, v18, v27
	v_cvt_pk_bf16_f32 v18, v25, v26
	v_cvt_pk_bf16_f32 v19, v28, v24
	v_cvt_pk_bf16_f32 v20, v29, v22
	v_cvt_pk_bf16_f32 v21, v23, v27
	ds_write_b128 v229, v[18:21] offset:9216
	ds_read2st64_b32 v[18:19], v107 offset0:1 offset1:3
	s_waitcnt lgkmcnt(0)
	v_sub_f32_e32 v18, v106, v18
	v_exp_f32_e32 v18, v18
	s_nop 0
	v_mul_f32_e32 v18, v19, v18
	v_mul_f32_e32 v19, v25, v18
	v_mul_f32_e32 v20, v26, v18
	v_mul_f32_e32 v21, v28, v18
	v_mul_f32_e32 v22, v22, v18
	v_mul_f32_e32 v23, v23, v18
	v_mul_f32_e32 v24, v24, v18
	v_mul_f32_e32 v25, v29, v18
	v_mul_f32_e32 v26, v27, v18
	v_cvt_pk_bf16_f32 v18, v19, v20
	v_cvt_pk_bf16_f32 v19, v21, v24
	v_cvt_pk_bf16_f32 v20, v25, v22
	v_cvt_pk_bf16_f32 v21, v23, v26
	ds_write_b128 v229, v[18:21] offset:27648
	s_waitcnt vmcnt(11)
	ds_write_b128 v224, v[66:69] offset:36864
	v_add_u32_e32 v18, 0x11800, v224
	s_waitcnt vmcnt(10)
	ds_write_b128 v18, v[70:73]
	s_waitcnt vmcnt(9)
	ds_write_b128 v224, v[74:77] offset:45568
	s_waitcnt vmcnt(8)
	ds_write_b128 v18, v[78:81] offset:8704
	s_waitcnt vmcnt(7)
	ds_write_b128 v224, v[82:85] offset:54272
	s_waitcnt vmcnt(6)
	ds_write_b128 v18, v[86:89] offset:17408
	s_waitcnt vmcnt(5)
	ds_write_b128 v224, v[90:93] offset:62976
	s_waitcnt vmcnt(4)
	ds_write_b128 v18, v[94:97] offset:26112
	s_cbranch_scc1 .LBB0_1304
	s_add_i32 s26, s92, 0x80
	s_mul_i32 s30, s26, 0x1800
	s_mul_hi_u32 s27, s26, 0x1800
	s_add_u32 s28, s84, s30
	s_addc_u32 s29, s85, s27
	v_lshl_add_u64 v[20:21], s[28:29], 0, v[138:139]
	global_load_dwordx4 v[50:53], v[20:21], off
	v_lshl_add_u64 v[18:19], s[28:29], 0, v[142:143]
	s_and_saveexec_b64 s[28:29], s[8:9]
	s_cbranch_execz .LBB0_1300
	v_lshl_add_u64 v[22:23], v[18:19], 0, v[158:159]
	global_load_dwordx4 v[58:61], v[22:23], off

; __device__ __forceinline__ float silu_f(float x) { return x * sigm(x); }
; #define GAS __attribute__((address_space(1)))
; #define LAS __attribute__((address_space(3)))
; __device__ __forceinline__ void ssd_stream(const Frame& F, const Args& A, int sidx) {
;     ...
;         {
;             GAS unsigned char* yb = YGg + (size_t)t0 * 4096;
;             float ssq = 0.f;
; #pragma unroll
;             for (int q4 = 0; q4 < 4; ++q4) {
;                 const int p0 = 32 * pt + 8 * q4 + 4 * hh;
;                 const v2u xw = *(LAS v2u*)(XT + lcol * XS_ + p0 * 2);
;                 const float y0 = (Y[4 * q4 + 0] + Dsk * bflo(xw.x)) * silu_f(bflo(zw[q4].x)), y1 = (Y[4 * q4 + 1] + Dsk * bfhi(xw.x)) * silu_f(bfhi(zw[q4].x));
.LBB0_1312:
	ds_read_b64 v[36:37], v226
	ds_read_b64 v[38:39], v226 offset:16
	ds_read_b64 v[40:41], v226 offset:32
	ds_read_b64 v[42:43], v226 offset:48
	v_lshl_add_u64 v[34:35], v[154:155], 0, s[64:65]
	v_and_b32_e32 v46, 32, v202
	v_lshrrev_b32_e32 v46, 2, v46
	v_add_co_u32_e32 v34, vcc, v34, v46
	v_mov_b32_e32 v44, v141
	v_addc_co_u32_e32 v35, vcc, 0, v35, vcc
	v_mov_b32_e32 v45, v141
	s_andn2_b64 vcc, exec, s[60:61]
	s_cbranch_vccnz .LZW_last
	s_waitcnt vmcnt(12)
	s_branch .LZW_go

; __device__ __forceinline__ unsigned cvt_pk_bf16(float lo, float hi) { unsigned r; asm volatile("v_cvt_pk_bf16_f32 %0, %1, %2" : "=v"(r) : "v"(lo), "v"(hi)); return r; }
; __device__ __forceinline__ float silu_f(float x) { return x * sigm(x); }
; #define GAS __attribute__((address_space(1)))
; #define LAS __attribute__((address_space(3)))
; __device__ __forceinline__ void ssd_stream(const Frame& F, const Args& A, int sidx) {
;     ...
;         {
;             GAS unsigned char* yb = YGg + (size_t)t0 * 4096;
;             float ssq = 0.f;
; #pragma unroll
;             for (int q4 = 0; q4 < 4; ++q4) {
;                 const int p0 = 32 * pt + 8 * q4 + 4 * hh;
;                 const v2u xw = *(LAS v2u*)(XT + lcol * XS_ + p0 * 2);
;                 const float y0 = (Y[4 * q4 + 0] + Dsk * bflo(xw.x)) * silu_f(bflo(zw[q4].x)), y1 = (Y[4 * q4 + 1] + Dsk * bfhi(xw.x)) * silu_f(bfhi(zw[q4].x));
;                 const float y2 = (Y[4 * q4 + 2] + Dsk * bflo(xw.y)) * silu_f(bflo(zw[q4].y)), y3 = (Y[4 * q4 + 3] + Dsk * bfhi(xw.y)) * silu_f(bfhi(zw[q4].y));
;                 ssq += (y0 * y0 + y1 * y1) + (y2 * y2 + y3 * y3);
;                 v2u o; o.x = pg8::cvt_pk_bf16(y0, y1); o.y = pg8::cvt_pk_bf16(y2, y3);
;                 *(GAS v2u*)(yb + 16 * q4 + zoff) = o;
;             }
;             ssq += __shfl_xor(ssq, 32);
;             if (hh == 0) *(GAS float*)(SSQg + (size_t)t0 * 256 + soff) = ssq;
.LZW_go:
	v_lshlrev_b32_e32 v98, 16, v184
	v_and_b32_e32 v99, 0xffff0000, v184
	v_lshlrev_b32_e32 v100, 16, v185
	v_and_b32_e32 v101, 0xffff0000, v185
	v_lshlrev_b32_e32 v102, 16, v182
	v_and_b32_e32 v103, 0xffff0000, v182
	v_lshlrev_b32_e32 v104, 16, v183
	v_and_b32_e32 v105, 0xffff0000, v183
	v_lshlrev_b32_e32 v106, 16, v180
	v_and_b32_e32 v107, 0xffff0000, v180
	v_lshlrev_b32_e32 v108, 16, v181
	v_and_b32_e32 v109, 0xffff0000, v181
	v_lshlrev_b32_e32 v110, 16, v178
	v_and_b32_e32 v111, 0xffff0000, v178
	v_lshlrev_b32_e32 v112, 16, v179
	v_and_b32_e32 v113, 0xffff0000, v179
	v_mul_f32_e32 v114, 0xbfb8aa3b, v98
	v_mul_f32_e32 v115, 0xbfb8aa3b, v99
	v_mul_f32_e32 v116, 0xbfb8aa3b, v100
	v_mul_f32_e32 v117, 0xbfb8aa3b, v101
	v_mul_f32_e32 v118, 0xbfb8aa3b, v102
	v_mul_f32_e32 v119, 0xbfb8aa3b, v103
	v_mul_f32_e32 v120, 0xbfb8aa3b, v104
	v_mul_f32_e32 v121, 0xbfb8aa3b, v105
	v_mul_f32_e32 v122, 0xbfb8aa3b, v106
	v_mul_f32_e32 v123, 0xbfb8aa3b, v107
	v_mul_f32_e32 v124, 0xbfb8aa3b, v108
	v_mul_f32_e32 v125, 0xbfb8aa3b, v109
	v_mul_f32_e32 v126, 0xbfb8aa3b, v110
	v_mul_f32_e32 v127, 0xbfb8aa3b, v111
	v_mul_f32_e32 v128, 0xbfb8aa3b, v112
	v_mul_f32_e32 v129, 0xbfb8aa3b, v113
	v_exp_f32_e32 v114, v114
	v_exp_f32_e32 v115, v115
	v_exp_f32_e32 v116, v116
	v_exp_f32_e32 v117, v117
	v_exp_f32_e32 v118, v118
	v_exp_f32_e32 v119, v119
	v_exp_f32_e32 v120, v120
	v_exp_f32_e32 v121, v121
	v_exp_f32_e32 v122, v122
	v_exp_f32_e32 v123, v123
	v_exp_f32_e32 v124, v124
	v_exp_f32_e32 v125, v125
	v_exp_f32_e32 v126, v126
	v_exp_f32_e32 v127, v127
	v_exp_f32_e32 v128, v128
	v_exp_f32_e32 v129, v129
	s_waitcnt lgkmcnt(0)
	v_lshlrev_b32_e32 v186, 16, v36
	v_and_b32_e32 v187, 0xffff0000, v36
	v_lshlrev_b32_e32 v188, 16, v37
	v_and_b32_e32 v189, 0xffff0000, v37
	v_lshlrev_b32_e32 v190, 16, v38
	v_and_b32_e32 v191, 0xffff0000, v38
	v_lshlrev_b32_e32 v192, 16, v39
	v_and_b32_e32 v193, 0xffff0000, v39
	v_lshlrev_b32_e32 v194, 16, v40
	v_and_b32_e32 v195, 0xffff0000, v40
	v_lshlrev_b32_e32 v196, 16, v41
	v_and_b32_e32 v197, 0xffff0000, v41
	v_lshlrev_b32_e32 v198, 16, v42
	v_and_b32_e32 v199, 0xffff0000, v42
	v_lshlrev_b32_e32 v200, 16, v43
	v_and_b32_e32 v201, 0xffff0000, v43
	v_add_f32_e32 v114, 1.0, v114
	v_add_f32_e32 v115, 1.0, v115
	v_add_f32_e32 v116, 1.0, v116
	v_add_f32_e32 v117, 1.0, v117
	v_add_f32_e32 v118, 1.0, v118
	v_add_f32_e32 v119, 1.0, v119
	v_add_f32_e32 v120, 1.0, v120
	v_add_f32_e32 v121, 1.0, v121
	v_add_f32_e32 v122, 1.0, v122
	v_add_f32_e32 v123, 1.0, v123
	v_add_f32_e32 v124, 1.0, v124
	v_add_f32_e32 v125, 1.0, v125
	v_add_f32_e32 v126, 1.0, v126
	v_add_f32_e32 v127, 1.0, v127
	v_add_f32_e32 v128, 1.0, v128
	v_add_f32_e32 v129, 1.0, v129
	v_rcp_f32_e32 v114, v114
	v_rcp_f32_e32 v115, v115
	v_rcp_f32_e32 v116, v116
	v_rcp_f32_e32 v117, v117
	v_rcp_f32_e32 v118, v118
	v_rcp_f32_e32 v119, v119
	v_rcp_f32_e32 v120, v120
	v_rcp_f32_e32 v121, v121
	v_rcp_f32_e32 v122, v122
	v_rcp_f32_e32 v123, v123
	v_rcp_f32_e32 v124, v124
	v_rcp_f32_e32 v125, v125
	v_rcp_f32_e32 v126, v126
	v_rcp_f32_e32 v127, v127
	v_rcp_f32_e32 v128, v128
	v_rcp_f32_e32 v129, v129
	v_pk_mul_f32 v[186:187], v[186:187], v[44:45]
	v_pk_mul_f32 v[188:189], v[188:189], v[44:45]
	v_pk_mul_f32 v[190:191], v[190:191], v[44:45]
	v_pk_mul_f32 v[192:193], v[192:193], v[44:45]
	v_pk_mul_f32 v[194:195], v[194:195], v[44:45]
	v_pk_mul_f32 v[196:197], v[196:197], v[44:45]
	v_pk_mul_f32 v[198:199], v[198:199], v[44:45]
	v_pk_mul_f32 v[200:201], v[200:201], v[44:45]
	v_pk_mul_f32 v[114:115], v[114:115], v[98:99]
	v_pk_mul_f32 v[116:117], v[116:117], v[100:101]
	v_pk_mul_f32 v[118:119], v[118:119], v[102:103]
	v_pk_mul_f32 v[120:121], v[120:121], v[104:105]
	v_pk_mul_f32 v[122:123], v[122:123], v[106:107]
	v_pk_mul_f32 v[124:125], v[124:125], v[108:109]
	v_pk_mul_f32 v[126:127], v[126:127], v[110:111]
	v_pk_mul_f32 v[128:129], v[128:129], v[112:113]
	v_pk_add_f32 v[18:19], v[18:19], v[186:187]
	v_pk_add_f32 v[20:21], v[20:21], v[188:189]
	v_pk_add_f32 v[22:23], v[22:23], v[190:191]
	v_pk_add_f32 v[24:25], v[24:25], v[192:193]
	v_pk_add_f32 v[26:27], v[26:27], v[194:195]
	v_pk_add_f32 v[28:29], v[28:29], v[196:197]
	v_pk_add_f32 v[30:31], v[30:31], v[198:199]
	v_pk_add_f32 v[32:33], v[32:33], v[200:201]
	v_pk_mul_f32 v[18:19], v[114:115], v[18:19]
	v_pk_mul_f32 v[20:21], v[116:117], v[20:21]
	v_pk_mul_f32 v[22:23], v[118:119], v[22:23]
	v_pk_mul_f32 v[24:25], v[120:121], v[24:25]
	v_pk_mul_f32 v[26:27], v[122:123], v[26:27]
	v_pk_mul_f32 v[28:29], v[124:125], v[28:29]
	v_pk_mul_f32 v[30:31], v[126:127], v[30:31]
	v_pk_mul_f32 v[32:33], v[128:129], v[32:33]
	v_cvt_pk_bf16_f32 v232, v18, v19
	v_cvt_pk_bf16_f32 v233, v20, v21
	v_cvt_pk_bf16_f32 v234, v22, v23
	v_cvt_pk_bf16_f32 v235, v24, v25
	v_cvt_pk_bf16_f32 v236, v26, v27
	v_cvt_pk_bf16_f32 v237, v28, v29
	v_cvt_pk_bf16_f32 v238, v30, v31
	v_cvt_pk_bf16_f32 v239, v32, v33
	v_mul_f32_e32 v130, v19, v19
	v_mul_f32_e32 v46, v21, v21
	v_mul_f32_e32 v131, v23, v23
	v_mul_f32_e32 v47, v25, v25
	v_mul_f32_e32 v132, v27, v27
	v_mul_f32_e32 v40, v29, v29
	v_mul_f32_e32 v133, v31, v31
	v_mul_f32_e32 v41, v33, v33
	v_fmac_f32_e32 v130, v18, v18
	v_fmac_f32_e32 v46, v20, v20
	v_fmac_f32_e32 v131, v22, v22
	v_fmac_f32_e32 v47, v24, v24
	v_fmac_f32_e32 v132, v26, v26
	v_fmac_f32_e32 v40, v28, v28
	v_fmac_f32_e32 v133, v30, v30
	v_fmac_f32_e32 v41, v32, v32
	v_add_f32_e32 v130, v130, v46
	v_add_f32_e32 v131, v131, v47
	v_add_f32_e32 v132, v132, v40
	v_add_f32_e32 v133, v133, v41
	v_permlane32_swap_b32_e32 v232, v234
	v_permlane32_swap_b32_e32 v233, v235
	v_permlane32_swap_b32_e32 v236, v238
	v_permlane32_swap_b32_e32 v237, v239
	v_add_f32_e32 v24, v130, v131
	v_add_f32_e32 v24, v24, v132
	v_mov_b32_e32 v19, v133
	global_store_dwordx4 v[34:35], v[232:235], off
	global_store_dwordx4 v[34:35], v[236:239], off offset:32
	v_and_b32_e32 v18, 64, v202
	v_xor_b32_e32 v20, 32, v202
	v_add_u32_e32 v21, 64, v18
	v_cmp_lt_i32_e32 vcc, v20, v21
	v_add_f32_e32 v19, v24, v19
	s_nop 0
	v_cndmask_b32_e32 v20, v202, v20, vcc
	v_lshlrev_b32_e32 v20, 2, v20
	ds_bpermute_b32 v20, v20, v19
	s_and_saveexec_b64 s[26:27], s[12:13]
	s_cbranch_execz .LBB0_1314
	s_lshl_b64 s[28:29], s[92:93], 8
	v_lshl_add_u64 v[22:23], v[156:157], 0, s[28:29]
	s_waitcnt lgkmcnt(0)
	v_add_f32_e32 v19, v19, v20
	global_store_dword v[22:23], v19, off
